# speedup vs baseline: 1.0025x; 1.0025x over previous
; __device__ __forceinline__ int sub_op() { return __builtin_amdgcn_readfirstlane((int)(threadIdx.x >> 8)); }
; #define LAS __attribute__((address_space(3)))
; __global__ void __launch_bounds__(512, 2) mega_kernel(Params p) {
;   __shared__ __attribute__((aligned(16))) char smem[2 * SMEM_BYTES + 16];
;   __shared__ uint4 xb_words;
;   if (threadIdx.x == 0) xb_words = make_uint4(0u, 0u, 0u, 0u);
;   __syncthreads();
;   const XcdBarrier xb = xcd_barrier_post(p.bar, (volatile LAS unsigned*)&xb_words, (unsigned)(p.nblk >> 1));
;   run_range<0, NPHASE>(p, smem + sub_op() * SMEM_BYTES, smem, xb);
_Z11mega_kernel6Params:
	s_load_dwordx4 s[4:7], s[0:1], 0x140
	v_readfirstlane_b32 vcc_lo, v0
	s_bfe_u32 vcc_lo, vcc_lo, 0x20008
	s_cmp_eq_u32 vcc_lo, 0
	s_cbranch_scc1 .Lprio_skip
	s_setprio 3
